# P4 work-queue order: long attention/sample tiles dequeued before short SSD state tiles
# speedup vs baseline: 1.0138x; 1.0138x over previous
.LBB0_774:
	s_or_b64 exec, exec, s[2:3]
	s_waitcnt lgkmcnt(0)
	s_barrier
	ds_read_b32 v0, v182
	s_movk_i32 s2, 0x476
	s_waitcnt lgkmcnt(0)
	v_cmp_lt_i32_e32 vcc, s2, v0
	v_readfirstlane_b32 s18, v0
	s_mov_b64 s[2:3], -1
	s_cbranch_vccnz .LBB0_769
	s_movk_i32 s98, 0x47
	s_cmpk_ge_u32 s18, 480
	s_cselect_b32 s98, 631, s98
	s_cmpk_ge_u32 s18, 496
	s_cselect_b32 s98, 599, s98
	s_cmpk_ge_u32 s18, 512
	s_cselect_b32 s98, 551, s98
	s_cmpk_ge_u32 s18, 544
	s_cselect_b32 s98, -544, s98
	s_cmpk_ge_u32 s18, 615
	s_cselect_b32 s98, -64, s98
	s_cmpk_ge_u32 s18, 1127
	s_cselect_b32 s98, 0, s98
	s_add_i32 s18, s18, s98
	s_cmpk_gt_i32 s18, 0x46
	s_cbranch_scc0 .LBB0_1018
	s_cmpk_gt_u32 s18, 0x226
	s_cbranch_scc0 .LBB0_1015
	s_cmpk_gt_u32 s18, 0x426
	s_cbranch_scc0 .LBB0_1029
	s_cmpk_gt_u32 s18, 0x446
	s_cbranch_scc0 .LBB0_1030
	s_cmpk_gt_u32 s18, 0x456
	s_cbranch_scc0 .LBB0_1031
	s_cmpk_gt_u32 s18, 0x466
	s_cbranch_scc0 .LBB0_877
	v_mov_b32_e32 v148, v252
	s_nop 0
	v_and_b32_e32 v149, 63, v148
	v_readfirstlane_b32 s6, v148
	s_ashr_i32 s30, s6, 6
	v_cmp_gt_u32_e32 vcc, 32, v149
	v_cmp_lt_u32_e64 s[40:41], 31, v149
	s_barrier
	s_and_saveexec_b64 s[2:3], s[40:41]
	s_xor_b64 s[2:3], exec, s[2:3]
	s_ashr_i32 s31, s30, 31
	s_or_saveexec_b64 s[2:3], s[2:3]
	s_add_i32 s8, s18, 0xfffffb99
	s_lshl_b32 s10, s8, 5
	s_add_i32 s9, s10, 0x8000
	v_mov_b32_e32 v0, 0
	v_mov_b64_e32 v[2:3], s[30:31]
	s_xor_b64 exec, exec, s[2:3]
	s_cbranch_execz .LBB0_787
	s_load_dwordx2 s[4:5], s[0:1], 0x60
	v_or_b32_e32 v0, s9, v149
	s_ashr_i32 s31, s30, 31
	v_lshlrev_b64 v[2:3], 5, v[0:1]
	s_lshl_b64 s[36:37], s[30:31], 2
	v_lshl_add_u64 v[2:3], s[12:13], 0, v[2:3]
	s_waitcnt lgkmcnt(0)
	s_add_u32 s4, s4, s36
	v_lshl_add_u64 v[2:3], v[2:3], 0, s[36:37]
	s_addc_u32 s5, s5, s37
	global_load_dword v0, v[2:3], off
	s_nop 0
	global_load_dword v2, v1, s[4:5]
	s_mov_b32 s4, 0x41a00000
	s_waitcnt vmcnt(0)
	v_add_f32_e32 v0, v0, v2
	v_cmp_nlt_f32_e64 s[40:41], s4, v0
	s_and_saveexec_b64 s[4:5], s[40:41]
	s_cbranch_execz .LBB0_786
	v_mul_f32_e32 v2, 0x3fb8aa3b, v0
	v_rndne_f32_e32 v3, v2
	s_mov_b32 s7, 0x3fb8aa3b
	v_sub_f32_e32 v4, v2, v3
	v_fma_f32 v2, v0, s7, -v2
	v_fmac_f32_e32 v2, 0x32a5705f, v0
	v_add_f32_e32 v2, v4, v2
	v_cvt_i32_f32_e32 v3, v3
	v_exp_f32_e32 v2, v2
	s_mov_b32 s7, 0xc2ce8ed0
	v_cmp_ngt_f32_e64 s[40:41], s7, v0
	s_mov_b32 s7, 0x3f2aaaab
	v_ldexp_f32 v2, v2, v3
	v_cndmask_b32_e64 v2, 0, v2, s[40:41]
	v_cmp_nlt_f32_e64 s[40:41], s80, v0
	s_nop 1
	v_cndmask_b32_e64 v0, v183, v2, s[40:41]
	v_add_f32_e32 v4, 1.0, v0
	v_add_f32_e32 v2, -1.0, v4
	v_sub_f32_e32 v3, v2, v4
	v_add_f32_e32 v3, 1.0, v3
	v_sub_f32_e32 v2, v0, v2
	v_add_f32_e32 v5, v2, v3
	v_frexp_mant_f32_e32 v6, v4
	v_cvt_f64_f32_e32 v[2:3], v4
	v_frexp_exp_i32_f64_e32 v2, v[2:3]
	v_cmp_gt_f32_e64 s[40:41], s7, v6
	s_mov_b32 s7, 0x3f317218
	s_nop 0
	v_subbrev_co_u32_e64 v10, s[40:41], 0, v2, s[40:41]
	v_sub_u32_e32 v2, 0, v10
	v_ldexp_f32 v3, v4, v2
	v_add_f32_e32 v4, -1.0, v3
	v_add_f32_e32 v6, 1.0, v3
	v_ldexp_f32 v2, v5, v2
	v_add_f32_e32 v5, 1.0, v4
	v_add_f32_e32 v7, -1.0, v6
	v_sub_f32_e32 v5, v3, v5
	v_sub_f32_e32 v3, v3, v7
	v_add_f32_e32 v5, v2, v5
	v_add_f32_e32 v2, v2, v3
	v_add_f32_e32 v11, v6, v2
	v_rcp_f32_e32 v13, v11
	v_sub_f32_e32 v3, v6, v11
	v_add_f32_e32 v12, v2, v3
	v_add_f32_e32 v3, v4, v5
	v_mul_f32_e32 v15, v3, v13
	v_sub_f32_e32 v2, v4, v3
	v_mul_f32_e32 v4, v11, v15
	v_fma_f32 v6, v15, v11, -v4
	v_fmac_f32_e32 v6, v15, v12
	v_add_f32_e32 v14, v5, v2
	v_add_f32_e32 v2, v4, v6
	v_sub_f32_e32 v5, v3, v2
	v_pk_add_f32 v[8:9], v[2:3], v[4:5] neg_lo:[0,1] neg_hi:[0,1]
	v_mov_b32_e32 v7, v2
	v_pk_add_f32 v[2:3], v[8:9], v[6:7] neg_lo:[0,1] neg_hi:[0,1]
	s_nop 0
	v_add_f32_e32 v3, v14, v3
	v_add_f32_e32 v2, v2, v3
	v_add_f32_e32 v3, v5, v2
	v_mul_f32_e32 v14, v13, v3
	v_mul_f32_e32 v4, v11, v14
	v_fma_f32 v6, v14, v11, -v4
	v_fmac_f32_e32 v6, v14, v12
	v_sub_f32_e32 v5, v5, v3
	v_add_f32_e32 v11, v2, v5
	v_add_f32_e32 v2, v4, v6
	v_sub_f32_e32 v5, v3, v2
	v_pk_add_f32 v[8:9], v[2:3], v[4:5] neg_lo:[0,1] neg_hi:[0,1]
	v_mov_b32_e32 v7, v2
	v_pk_add_f32 v[2:3], v[8:9], v[6:7] neg_lo:[0,1] neg_hi:[0,1]
	s_nop 0
	v_add_f32_e32 v3, v11, v3
	v_add_f32_e32 v2, v2, v3
	v_add_f32_e32 v3, v15, v14
	v_add_f32_e32 v2, v5, v2
	v_sub_f32_e32 v4, v3, v15
	v_mul_f32_e32 v2, v13, v2
	v_sub_f32_e32 v4, v14, v4
	v_add_f32_e32 v4, v4, v2
	v_add_f32_e32 v6, v3, v4
	v_mul_f32_e32 v7, v6, v6
	v_fmamk_f32 v2, v7, 0x3e9b6dac, v178
	v_fmaak_f32 v165, v7, v2, 0x3f2aaada
	v_cvt_f32_i32_e32 v2, v10
	v_sub_f32_e32 v3, v6, v3
	v_sub_f32_e32 v3, v4, v3
	v_ldexp_f32 v8, v3, 1
	v_mul_f32_e32 v3, v6, v7
	v_ldexp_f32 v5, v6, 1
	v_pk_mul_f32 v[6:7], v[2:3], v[164:165]
	s_nop 0
	v_fma_f32 v4, v2, s7, -v6
	v_fmac_f32_e32 v4, 0xb102e308, v2
	v_pk_add_f32 v[2:3], v[6:7], v[4:5]
	s_mov_b32 s7, 0x7f800000
	v_sub_f32_e32 v5, v3, v5
	v_sub_f32_e32 v5, v7, v5
	v_add_f32_e32 v9, v8, v5
	v_mov_b32_e32 v8, v6
	v_pk_add_f32 v[6:7], v[2:3], v[6:7] neg_lo:[0,1] neg_hi:[0,1]
	v_pk_add_f32 v[10:11], v[2:3], v[8:9]
	v_mov_b32_e32 v5, v2
	v_mov_b32_e32 v7, v11
	v_pk_add_f32 v[12:13], v[4:5], v[6:7] neg_lo:[0,1] neg_hi:[0,1]
	v_pk_add_f32 v[4:5], v[4:5], v[6:7]
	v_mov_b32_e32 v8, v9
	v_pk_add_f32 v[6:7], v[4:5], v[2:3] op_sel:[1,0] op_sel_hi:[0,1] neg_lo:[0,1] neg_hi:[0,1]
	v_pk_add_f32 v[14:15], v[10:11], v[6:7] op_sel_hi:[1,0] neg_lo:[0,1] neg_hi:[0,1]
	v_mov_b32_e32 v10, v11
	v_mov_b32_e32 v11, v5
	v_pk_mov_b32 v[6:7], v[2:3], v[6:7] op_sel:[1,0]
	v_mov_b32_e32 v9, v2
	v_pk_add_f32 v[6:7], v[10:11], v[6:7] neg_lo:[0,1] neg_hi:[0,1]
	v_mov_b32_e32 v14, v12
	v_pk_add_f32 v[2:3], v[8:9], v[6:7] neg_lo:[0,1] neg_hi:[0,1]
	v_mov_b32_e32 v13, v5
	v_pk_add_f32 v[6:7], v[14:15], v[2:3]
	v_cmp_neq_f32_e64 s[40:41], s7, v0
	v_pk_add_f32 v[8:9], v[6:7], v[6:7] op_sel:[0,1] op_sel_hi:[1,0]
	s_mov_b32 s7, 0x33800000
	v_pk_add_f32 v[4:5], v[4:5], v[8:9] op_sel:[1,0] op_sel_hi:[0,1]
	v_mov_b32_e32 v7, v4
	v_pk_add_f32 v[10:11], v[6:7], v[12:13] neg_lo:[0,1] neg_hi:[0,1]
	v_mov_b32_e32 v3, v8
	v_sub_f32_e32 v5, v6, v10
	v_pk_add_f32 v[2:3], v[2:3], v[10:11] neg_lo:[0,1] neg_hi:[0,1]
	v_sub_f32_e32 v5, v12, v5
	v_add_f32_e32 v2, v2, v5
	v_add_f32_e32 v2, v2, v3
	v_add_f32_e32 v2, v4, v2
	v_cndmask_b32_e64 v2, v183, v2, s[40:41]
	v_cmp_lt_f32_e64 s[40:41], |v0|, s7
	s_nop 1
	v_cndmask_b32_e64 v0, v2, v0, s[40:41]

	.amdhsa_kernel _Z10hybrid_fwd6Params
		.amdhsa_group_segment_fixed_size 0
		.amdhsa_private_segment_fixed_size 0
		.amdhsa_kernarg_size 472
		.amdhsa_user_sgpr_count 2
		.amdhsa_user_sgpr_dispatch_ptr 0
		.amdhsa_user_sgpr_queue_ptr 0
		.amdhsa_user_sgpr_kernarg_segment_ptr 1
		.amdhsa_user_sgpr_dispatch_id 0
		.amdhsa_user_sgpr_kernarg_preload_length 0
		.amdhsa_user_sgpr_kernarg_preload_offset 0
		.amdhsa_user_sgpr_private_segment_size 0
		.amdhsa_uses_dynamic_stack 0
		.amdhsa_enable_private_segment 0
		.amdhsa_system_sgpr_workgroup_id_x 1
		.amdhsa_system_sgpr_workgroup_id_y 0
		.amdhsa_system_sgpr_workgroup_id_z 0
		.amdhsa_system_sgpr_workgroup_info 0
		.amdhsa_system_vgpr_workitem_id 2
		.amdhsa_next_free_vgpr 256
		.amdhsa_next_free_sgpr 102
		.amdhsa_accum_offset 256
		.amdhsa_reserve_vcc 1
		.amdhsa_float_round_mode_32 0
		.amdhsa_float_round_mode_16_64 0
		.amdhsa_float_denorm_mode_32 3
		.amdhsa_float_denorm_mode_16_64 3
		.amdhsa_dx10_clamp 1
		.amdhsa_ieee_mode 1
		.amdhsa_fp16_overflow 0
		.amdhsa_tg_split 0
		.amdhsa_exception_fp_ieee_invalid_op 0
		.amdhsa_exception_fp_denorm_src 0
		.amdhsa_exception_fp_ieee_div_zero 0
		.amdhsa_exception_fp_ieee_overflow 0
		.amdhsa_exception_fp_ieee_underflow 0
		.amdhsa_exception_fp_ieee_inexact 0
		.amdhsa_exception_int_div_zero 0
	.end_amdhsa_kernel

amdhsa.kernels:
  - .agpr_count:     0
    .args:
      - .offset:         0
        .size:           216
        .value_kind:     by_value
      - .offset:         216
        .size:           4
        .value_kind:     hidden_block_count_x
      - .offset:         220
        .size:           4
        .value_kind:     hidden_block_count_y
      - .offset:         224
        .size:           4
        .value_kind:     hidden_block_count_z
      - .offset:         228
        .size:           2
        .value_kind:     hidden_group_size_x
      - .offset:         230
        .size:           2
        .value_kind:     hidden_group_size_y
      - .offset:         232
        .size:           2
        .value_kind:     hidden_group_size_z
      - .offset:         234
        .size:           2
        .value_kind:     hidden_remainder_x
      - .offset:         236
        .size:           2
        .value_kind:     hidden_remainder_y
      - .offset:         238
        .size:           2
        .value_kind:     hidden_remainder_z
      - .offset:         256
        .size:           8
        .value_kind:     hidden_global_offset_x
      - .offset:         264
        .size:           8
        .value_kind:     hidden_global_offset_y
      - .offset:         272
        .size:           8
        .value_kind:     hidden_global_offset_z
      - .offset:         280
        .size:           2
        .value_kind:     hidden_grid_dims
      - .offset:         304
        .size:           8
        .value_kind:     hidden_multigrid_sync_arg
      - .offset:         336
        .size:           4
        .value_kind:     hidden_dynamic_lds_size
    .group_segment_fixed_size: 0
    .kernarg_segment_align: 8
    .kernarg_segment_size: 472
    .language:       OpenCL C
    .language_version:
      - 2
      - 0
    .max_flat_workgroup_size: 512
    .name:           _Z10hybrid_fwd6Params
    .private_segment_fixed_size: 0
    .sgpr_count:     108
    .sgpr_spill_count: 171
    .symbol:         _Z10hybrid_fwd6Params.kd
    .uniform_work_group_size: 1
    .uses_dynamic_stack: false
    .vgpr_count:     256
    .vgpr_spill_count: 0
    .wavefront_size: 64
